# dense loop: Q-fragment vmcnt waits hoisted out of the tile loop so the K/V staging loads stay in flight until their LDS write (waitcnt placement)
# baseline (speedup 1.0000x reference)
; #define LAS __attribute__((address_space(3)))
; __device__ __forceinline__ int otid(int wv) { int l; asm volatile("v_mbcnt_lo_u32_b32 %0, -1, 0\n\tv_mbcnt_hi_u32_b32 %0, -1, %0" : "=v"(l)); return wv * 64 + l; }
; #define B_LOAD(t) do { _Pragma("unroll") for (int i = 0; i < 2; ++i) { const size_t gofs = (tokbase + 64 * (t) + srow_ + 32 * i) * 256 + sch * 16; \
;             kreg[i] = *(const u32x4*)(BK + gofs); vreg[i] = *(const u32x4*)(BV + gofs); } } while (0)
; #define B_WRITE(st) do { _Pragma("unroll") for (int i = 0; i < 2; ++i) { *(LAS u32x4*)(lds + (st) * A_STG + (srow_ + 32 * i) * A_KROW + sch * 16) = kreg[i]; \
;             *(LAS u32x4*)(lds + (st) * A_STG + A_KBUF + (srow_ + 32 * i) * A_VROW + sch * 16) = vreg[i]; } } while (0)
; __device__ __forceinline__ void phaseB(const Params& p, LAS unsigned char* lds, int wv) {
;     ...
;         const int tid = otid(wv);
;         const int lane = tid & 63, wid = __builtin_amdgcn_readfirstlane(tid >> 6), r32 = lane & 31, hi = lane >> 5; (void)r32; (void)hi; (void)wid;
;             LAS float* linv = (LAS float*)(lds + B_LINV) + wid * 64;
;             const int qg = wid & 1, hp = wid >> 1, g = hp >> 1;
;             const int qpos = q0 + 32 * qg + r32, qw0 = q0 + 32 * qg;
;             const unsigned char* Qp0 = BQ + (tokbase + qpos) * 1024 + (2 * hp) * 128 + hi * 16;
;             const LAS unsigned* mrow = (const LAS unsigned*)(lds + B_MASK) + (32 * qg + r32) * B_MROW;
;             bf16x8 qf2[2][4];
; #pragma unroll
;             for (int hh = 0; hh < 2; ++hh)
; #pragma unroll
;                 for (int ds = 0; ds < 4; ++ds) qf2[hh][ds] = *(const bf16x8*)(Qp0 + hh * 128 + 32 * ds);
;             f32x16 O[2][2];
; #pragma unroll
;             for (int hh = 0; hh < 2; ++hh)
; #pragma unroll
;                 for (int db = 0; db < 2; ++db)
; #pragma unroll
;                     for (int r = 0; r < 16; ++r) O[hh][db][r] = 0.f;
;             float l0 = 0.f, l1 = 0.f;
;             u32x4 kreg[2], vreg[2];
;             const int srow_ = tid >> 4, sch = tid & 15;
;     ...
;             B_LOAD(0); B_WRITE(0);
;             __syncthreads();
; #pragma unroll 1
.LBB0_735:
	v_readlane_b32 s84, v247, 11
	s_waitcnt lgkmcnt(0)
	s_barrier
	v_mbcnt_lo_u32_b32 v8, -1, 0
	v_mbcnt_hi_u32_b32 v8, -1, v8
	v_readlane_b32 s30, v247, 50
	v_add_u32_e32 v9, s84, v8
	v_ashrrev_i32_e32 v0, 4, v9
	v_ashrrev_i32_e32 v1, 31, v0
	v_readlane_b32 s31, v247, 51
	v_lshlrev_b32_e32 v4, 4, v8
	v_and_b32_e32 v10, 0xf0, v4
	v_lshl_add_u64 v[2:3], v[0:1], 0, s[30:31]
	v_lshlrev_b64 v[2:3], 8, v[2:3]
	v_readlane_b32 s2, v247, 20
	v_readlane_b32 s4, v247, 22
	v_or_b32_e32 v2, v2, v10
	v_readlane_b32 s3, v247, 21
	v_readlane_b32 s5, v247, 23
	s_mov_b64 s[0:1], 0x2000
	v_lshl_add_u64 v[4:5], s[2:3], 0, v[2:3]
	v_lshl_add_u64 v[6:7], s[4:5], 0, v[2:3]
	v_lshl_add_u64 v[2:3], v[2:3], 0, s[0:1]
	global_load_dwordx4 v[160:163], v[4:5], off
	global_load_dwordx4 v[164:167], v[6:7], off
	v_lshl_add_u64 v[4:5], s[2:3], 0, v[2:3]
	v_lshl_add_u64 v[2:3], s[4:5], 0, v[2:3]
	global_load_dwordx4 v[168:171], v[4:5], off
	global_load_dwordx4 v[172:175], v[2:3], off
	s_lshl_b32 s2, s33, 14
	v_lshlrev_b32_e32 v3, 1, v8
	v_lshrrev_b32_e32 v4, 1, v8
	v_readfirstlane_b32 s8, v9
	v_readlane_b32 s3, v247, 35
	v_bfe_u32 v233, v8, 5, 1
	v_and_b32_e32 v5, 19, v8
	s_add_u32 s11, s2, 0x4000
	v_and_b32_e32 v3, 8, v3
	v_and_b32_e32 v4, 4, v4
	s_lshr_b32 s2, s8, 1
	s_ashr_i32 s6, s8, 6
	v_mov_b32_e32 v2, s3
	s_movk_i32 s3, 0x110
	s_movk_i32 s4, 0x140
	v_and_b32_e32 v234, 63, v8
	v_and_b32_e32 v232, 31, v8
	v_lshrrev_b32_e32 v6, 2, v8
	v_and_b32_e32 v7, 16, v8
	v_lshlrev_b32_e32 v8, 2, v8
	v_lshlrev_b32_e32 v235, 3, v233
	s_ashr_i32 s7, s8, 8
	v_or3_b32 v3, v5, v4, v3
	s_and_b32 s9, s2, 32
	s_and_b32 s10, s6, -2
	v_readlane_b32 s6, v247, 42
	s_movk_i32 s5, 0x208
	v_and_b32_e32 v8, 12, v8
	v_mul_lo_u32 v237, v0, s3
	v_mul_lo_u32 v238, v0, s4
	v_and_or_b32 v4, v6, 3, v235
	s_lshl_b32 s3, s7, 6
	v_mul_u32_u24_e32 v239, 0x110, v3
	s_or_b32 s13, s9, s6
	v_or_b32_e32 v3, s9, v232
	s_mul_i32 s4, s10, 0x500
	v_mul_u32_u24_e32 v240, 0x140, v4
	v_or3_b32 v4, s3, v7, v8
	v_or_b32_e32 v7, s13, v232
	s_add_i32 s14, s4, 0
	v_mad_u32_u24 v242, v3, s5, v2
	v_readlane_b32 s4, v247, 18
	s_lshl_b32 s2, s10, 7
	v_add_lshl_u32 v208, v7, s30, 10
	v_readlane_b32 s5, v247, 19
	s_ashr_i32 s3, s2, 31
	v_readlane_b32 s34, v247, 49
	v_lshl_add_u64 v[2:3], s[4:5], 0, v[208:209]
	v_lshlrev_b32_e32 v208, 4, v233
	v_lshl_add_u64 v[2:3], v[2:3], 0, s[2:3]
	v_lshl_add_u64 v[2:3], v[2:3], 0, v[208:209]
	global_load_dwordx4 v[176:179], v[2:3], off
	global_load_dwordx4 v[180:183], v[2:3], off offset:32
	global_load_dwordx4 v[184:187], v[2:3], off offset:64
	global_load_dwordx4 v[188:191], v[2:3], off offset:96
	global_load_dwordx4 v[192:195], v[2:3], off offset:128
	global_load_dwordx4 v[196:199], v[2:3], off offset:160
	global_load_dwordx4 v[200:203], v[2:3], off offset:192
	global_load_dwordx4 v[204:207], v[2:3], off offset:224
	v_add_u32_e32 v236, 0, v10
	v_readlane_b32 s2, v247, 1
	s_lshl_b32 s0, s34, 8
	v_add_u32_e32 v6, v236, v237
	v_readlane_b32 s3, v247, 2
	s_mov_b32 s1, s31
	s_and_b32 s0, s0, 0xf00000
	v_add_u32_e32 v9, v236, v238
	v_lshlrev_b64 v[0:1], 8, v[0:1]
	v_lshl_add_u64 v[0:1], s[0:1], 0, v[0:1]
	s_waitcnt vmcnt(11)
	ds_write_b128 v6, v[160:163]
	s_waitcnt vmcnt(10)
	ds_write_b128 v9, v[164:167] offset:17408
	s_waitcnt vmcnt(9)
	ds_write_b128 v6, v[168:171] offset:8704
	s_waitcnt vmcnt(8)
	ds_write_b128 v9, v[172:175] offset:27648
	s_waitcnt lgkmcnt(0)
	s_barrier
	s_load_dwordx2 s[82:83], s[2:3], 0xa8
	v_readlane_b32 s26, v247, 38
	v_sub_u32_e32 v5, v235, v232
	v_or_b32_e32 v0, v0, v10
	v_readlane_b32 s27, v247, 39
	v_subrev_u32_e32 v5, s9, v5
	v_readlane_b32 s28, v247, 40
	v_lshl_add_u64 v[210:211], s[26:27], 0, v[0:1]
	v_mov_b32_e32 v0, 0
	s_lshl_b32 s12, s7, 7
	v_lshlrev_b32_e32 v241, 1, v4
	s_add_i32 s14, s14, 0x12800
	v_subrev_u32_e32 v243, s6, v5
	s_mov_b32 s15, 0
	s_mov_b64 s[0:1], 0
	s_movk_i32 s16, 0xb0
	v_mov_b32_e32 v1, v0
	v_mov_b32_e32 v2, v0
	v_mov_b32_e32 v3, v0
	v_mov_b32_e32 v4, v0
	v_mov_b32_e32 v5, v0
	v_mov_b32_e32 v6, v0
	v_mov_b32_e32 v7, v0
	v_mov_b32_e32 v8, v0
	v_mov_b32_e32 v9, v0
	v_mov_b32_e32 v10, v0
	v_mov_b32_e32 v11, v0
	v_mov_b32_e32 v12, v0
	v_mov_b32_e32 v13, v0
	v_mov_b32_e32 v14, v0
	v_mov_b32_e32 v15, v0
	v_mov_b32_e32 v16, v0
	v_mov_b32_e32 v17, v0
	v_mov_b32_e32 v18, v0
	v_mov_b32_e32 v19, v0
	v_mov_b32_e32 v20, v0
	v_mov_b32_e32 v21, v0
	v_mov_b32_e32 v22, v0
	v_mov_b32_e32 v23, v0
	v_mov_b32_e32 v24, v0
	v_mov_b32_e32 v25, v0
	v_mov_b32_e32 v26, v0
	v_mov_b32_e32 v27, v0
	v_mov_b32_e32 v28, v0
	v_mov_b32_e32 v29, v0
	v_mov_b32_e32 v30, v0
	v_mov_b32_e32 v31, v0
	v_mov_b32_e32 v32, v0
	v_mov_b32_e32 v33, v0
	v_mov_b32_e32 v34, v0
	v_mov_b32_e32 v35, v0
	v_mov_b32_e32 v36, v0
	v_mov_b32_e32 v37, v0
	v_mov_b32_e32 v38, v0
	v_mov_b32_e32 v39, v0
	v_mov_b32_e32 v40, v0
	v_mov_b32_e32 v41, v0
	v_mov_b32_e32 v42, v0
	v_mov_b32_e32 v43, v0
	v_mov_b32_e32 v44, v0
	v_mov_b32_e32 v45, v0
	v_mov_b32_e32 v46, v0
	v_mov_b32_e32 v47, v0
	v_mov_b32_e32 v48, v0
	v_mov_b32_e32 v49, v0
	v_mov_b32_e32 v50, v0
	v_mov_b32_e32 v51, v0
	v_mov_b32_e32 v52, v0
	v_mov_b32_e32 v53, v0
	v_mov_b32_e32 v54, v0
	v_mov_b32_e32 v55, v0
	v_mov_b32_e32 v56, v0
	v_mov_b32_e32 v57, v0
	v_mov_b32_e32 v58, v0
	v_mov_b32_e32 v59, v0
	v_mov_b32_e32 v60, v0
	v_mov_b32_e32 v61, v0
	v_mov_b32_e32 v62, v0
	v_mov_b32_e32 v63, v0
	v_mov_b32_e32 v212, v0
	v_mov_b32_e32 v213, v0
	v_readlane_b32 s85, v246, 19
	v_readlane_b32 s86, v247, 36
	v_readlane_b32 s87, v247, 37
	v_readlane_b32 s44, v247, 52
	v_readlane_b32 s29, v247, 41
	s_waitcnt vmcnt(0)
	s_branch .LBB0_737

; #define LAS __attribute__((address_space(3)))
; __device__ __forceinline__ void phaseB(const Params& p, LAS unsigned char* lds, int wv) {
;     ...
;                 { const unsigned w0 = mrow[2 * t] >> (8 * hi), w1 = mrow[2 * t + 1] >> (8 * hi);
;                   selm = (w0 & 0xffu) | ((w0 >> 8) & 0xff00u) | ((w1 & 0xffu) << 16) | ((w1 << 8) & 0xff000000u); }
;                 float sacc0 = 0.f, sacc1 = 0.f;
; #pragma unroll
;                 for (int hf = 0; hf < 2; ++hf) {
;                     f32x16 s0, s1;
; #pragma unroll
;                     for (int r = 0; r < 16; ++r) { const float cm = ((selm >> (16 * hf + r)) & 1u) ? 0.f : -1e30f; s0[r] = cm; s1[r] = cm; }
;                     const LAS unsigned char* kp = Kb + (32 * hf + pi32(r32)) * A_KROW + g * 128 + hi * 16;
; #pragma unroll
;                     for (int ds = 0; ds < 4; ++ds) { const bf16x8 kf = *(const LAS bf16x8*)(kp + 32 * ds);
;                         s0 = __builtin_amdgcn_mfma_f32_32x32x16_bf16(kf, qf2[0][ds], s0, 0, 0, 0); s1 = __builtin_amdgcn_mfma_f32_32x32x16_bf16(kf, qf2[1][ds], s1, 0, 0, 0); }
;                     if (!near) {
; #pragma unroll
;                         for (int r = 0; r < 16; ++r) { s0[r] = __builtin_amdgcn_exp2f(s0[r]); s1[r] = __builtin_amdgcn_exp2f(s1[r]); }
.LBB0_739:
	v_add_u32_e32 v64, -4, v242
	ds_read_b64 v[128:129], v64
	s_cmp_le_u32 s16, s13
	s_cselect_b64 s[4:5], -1, 0
	s_bitcmp1_b32 s15, 0
	s_cselect_b32 s6, 0x9400, 0
	s_add_i32 s17, s6, 0
	s_add_i32 s6, s17, s12
	v_add_u32_e32 v64, s6, v208
	s_mov_b64 s[6:7], -1
	s_waitcnt lgkmcnt(0)
	v_lshrrev_b32_e32 v68, v235, v128
	v_add_u32_e32 v128, v64, v239
	ds_read_b128 v[64:67], v128
	v_bfe_i32 v96, v68, 0, 1
	v_bfe_i32 v97, v68, 1, 1
	v_bfe_i32 v98, v68, 2, 1
	v_bfe_i32 v99, v68, 3, 1
	v_bfe_i32 v100, v68, 4, 1
	v_bfe_i32 v101, v68, 5, 1
	v_bfe_i32 v102, v68, 6, 1
	v_bfe_i32 v103, v68, 7, 1
	v_bfe_i32 v104, v68, 16, 1
	v_bfe_i32 v105, v68, 17, 1
	v_bfe_i32 v106, v68, 18, 1
	v_bfe_i32 v107, v68, 19, 1
	v_bfe_i32 v108, v68, 20, 1
	v_bfe_i32 v109, v68, 21, 1
	v_bfe_i32 v110, v68, 22, 1
	v_bfe_i32 v111, v68, 23, 1
	ds_read_b128 v[68:71], v128 offset:32
	v_bfi_b32 v96, v96, 0, v231
	v_bfi_b32 v97, v97, 0, v231
	v_bfi_b32 v98, v98, 0, v231
	v_bfi_b32 v99, v99, 0, v231
	v_bfi_b32 v100, v100, 0, v231
	v_bfi_b32 v101, v101, 0, v231
	v_bfi_b32 v102, v102, 0, v231
	v_bfi_b32 v103, v103, 0, v231
	v_bfi_b32 v104, v104, 0, v231
	v_bfi_b32 v105, v105, 0, v231
	v_bfi_b32 v106, v106, 0, v231
	v_bfi_b32 v107, v107, 0, v231
	v_bfi_b32 v108, v108, 0, v231
	v_bfi_b32 v109, v109, 0, v231
	v_bfi_b32 v110, v110, 0, v231
	v_bfi_b32 v111, v111, 0, v231
	s_and_b64 vcc, exec, s[4:5]
	s_waitcnt lgkmcnt(1)
	v_mfma_f32_32x32x16_bf16 v[112:127], v[64:67], v[176:179], v[96:111]
	v_mfma_f32_32x32x16_bf16 v[96:111], v[64:67], v[192:195], v[96:111]
	s_waitcnt lgkmcnt(0)
	v_mfma_f32_32x32x16_bf16 v[112:127], v[68:71], v[180:183], v[112:127]
	v_mfma_f32_32x32x16_bf16 v[96:111], v[68:71], v[196:199], v[96:111]
	ds_read_b128 v[64:67], v128 offset:64
	ds_read_b128 v[68:71], v128 offset:96
	s_waitcnt lgkmcnt(1)
	v_mfma_f32_32x32x16_bf16 v[112:127], v[64:67], v[184:187], v[112:127]
	v_mfma_f32_32x32x16_bf16 v[96:111], v[64:67], v[200:203], v[96:111]
	s_waitcnt lgkmcnt(0)
	v_mfma_f32_32x32x16_bf16 v[112:127], v[68:71], v[188:191], v[112:127]
	v_mfma_f32_32x32x16_bf16 v[96:111], v[68:71], v[204:207], v[96:111]
	s_cbranch_vccz .LBB0_741
	s_nop 8
	v_exp_f32_e32 v64, v112
	s_nop 0
	v_exp_f32_e32 v80, v96
	v_exp_f32_e32 v65, v113
	v_exp_f32_e32 v81, v97
	v_exp_f32_e32 v66, v114
	v_exp_f32_e32 v82, v98
	v_exp_f32_e32 v67, v115
	v_exp_f32_e32 v83, v99
	v_exp_f32_e32 v68, v116
	v_exp_f32_e32 v84, v100
	v_exp_f32_e32 v69, v117
	v_exp_f32_e32 v85, v101
	v_exp_f32_e32 v70, v118
	v_exp_f32_e32 v86, v102
	v_exp_f32_e32 v71, v119
	v_exp_f32_e32 v87, v103
	v_exp_f32_e32 v72, v120
	v_exp_f32_e32 v88, v104
	v_exp_f32_e32 v73, v121
	v_exp_f32_e32 v89, v105
	v_exp_f32_e32 v74, v122
	v_exp_f32_e32 v90, v106
	v_exp_f32_e32 v75, v123
	v_exp_f32_e32 v91, v107
	v_exp_f32_e32 v76, v124
	v_exp_f32_e32 v92, v108
	v_exp_f32_e32 v77, v125
	v_exp_f32_e32 v93, v109
	v_exp_f32_e32 v78, v126
	v_exp_f32_e32 v94, v110
	v_exp_f32_e32 v79, v127
	s_mov_b64 s[6:7], 0

; __device__ __forceinline__ unsigned cvt_pk_bf16(float lo, float hi) { unsigned r; asm volatile("v_cvt_pk_bf16_f32 %0, %1, %2" : "=v"(r) : "v"(lo), "v"(hi)); return r; }
; #define LAS __attribute__((address_space(3)))
; #define B_WRITE(st) do { _Pragma("unroll") for (int i = 0; i < 2; ++i) { *(LAS u32x4*)(lds + (st) * A_STG + (srow_ + 32 * i) * A_KROW + sch * 16) = kreg[i]; \
;             *(LAS u32x4*)(lds + (st) * A_STG + A_KBUF + (srow_ + 32 * i) * A_VROW + sch * 16) = vreg[i]; } } while (0)
; __device__ __forceinline__ void phaseB(const Params& p, LAS unsigned char* lds, int wv) {
;     ...
;                     for (int r = 0; r < 16; ++r) { sacc0 += s0[r]; sacc1 += s1[r]; }
; #pragma unroll
;                     for (int jj = 0; jj < 2; ++jj) {
;                         const int j = 2 * hf + jj, rb = 8 * jj;
;                         u32x4 pw0, pw1;
;                         pw0.x = cvt_pk_bf16(s0[rb], s0[rb + 1]); pw0.y = cvt_pk_bf16(s0[rb + 2], s0[rb + 3]); pw0.z = cvt_pk_bf16(s0[rb + 4], s0[rb + 5]); pw0.w = cvt_pk_bf16(s0[rb + 6], s0[rb + 7]);
;                         pw1.x = cvt_pk_bf16(s1[rb], s1[rb + 1]); pw1.y = cvt_pk_bf16(s1[rb + 2], s1[rb + 3]); pw1.z = cvt_pk_bf16(s1[rb + 4], s1[rb + 5]); pw1.w = cvt_pk_bf16(s1[rb + 6], s1[rb + 7]);
;                         const bf16x8 pa0 = __builtin_bit_cast(bf16x8, pw0), pa1 = __builtin_bit_cast(bf16x8, pw1);
;                         const LAS unsigned char* vp = Vb + (16 * j + 8 * hi + ((lane & 15) >> 2)) * A_VROW + (g * 64 + 16 * ((lane >> 4) & 1) + 4 * (lane & 3)) * 2;
; #pragma unroll
;                         for (int db = 0; db < 2; ++db) {
;                             const s16x4 lo = vtr(vp + db * 64), hv = vtr(vp + 4 * A_VROW + db * 64);
;                             const bf16x8 vf = (bf16x8){lo[0], lo[1], lo[2], lo[3], hv[0], hv[1], hv[2], hv[3]};
;                             O[0][db] = __builtin_amdgcn_mfma_f32_32x32x16_bf16(pa0, vf, O[0][db], 0, 0, 0);
;                             O[1][db] = __builtin_amdgcn_mfma_f32_32x32x16_bf16(pa1, vf, O[1][db], 0, 0, 0);
;                         }
;                     }
;                     __builtin_amdgcn_sched_barrier(0);
;                 }
;                 l0 += sacc0; l1 += sacc1;
;                 if (t + 1 < NT) B_WRITE((t + 1) & 1);
.LBB0_747:
	v_cvt_pk_bf16_f32 v96, v112, v113
	v_cvt_pk_bf16_f32 v97, v114, v115
	v_cvt_pk_bf16_f32 v98, v116, v117
	v_cvt_pk_bf16_f32 v99, v118, v119
	v_cvt_pk_bf16_f32 v100, v128, v129
	v_cvt_pk_bf16_f32 v101, v130, v131
	v_cvt_pk_bf16_f32 v102, v132, v133
	v_cvt_pk_bf16_f32 v103, v134, v135
	s_nop 8
	ds_read_b64_tr_b16 v[104:105], v245 offset:27648
	ds_read_b64_tr_b16 v[106:107], v245 offset:28928
	ds_read_b64_tr_b16 v[146:147], v245 offset:28992
	ds_read_b64_tr_b16 v[144:145], v245 offset:27712
	s_waitcnt lgkmcnt(2)
	v_mfma_f32_32x32x16_bf16 v[48:63], v[96:99], v[104:107], v[48:63]
	v_add_f32_e32 v64, v64, v112
	v_add_f32_e32 v65, v65, v128
	v_add_f32_e32 v64, v64, v113
	v_add_f32_e32 v65, v65, v129
	v_exp_f32_e32 v95, v111
	s_add_i32 s15, s15, 1
	v_mfma_f32_32x32x16_bf16 v[16:31], v[100:103], v[104:107], v[16:31]
	v_add_f32_e32 v64, v64, v114
	v_add_f32_e32 v65, v65, v130
	v_add_f32_e32 v64, v64, v115
	v_add_f32_e32 v65, v65, v131
	s_waitcnt lgkmcnt(0)
	v_mfma_f32_32x32x16_bf16 v[32:47], v[96:99], v[144:147], v[32:47]
	v_add_f32_e32 v64, v64, v116
	v_add_f32_e32 v65, v65, v132
	v_add_f32_e32 v64, v64, v117
	v_add_f32_e32 v65, v65, v133
	v_cvt_pk_bf16_f32 v96, v120, v121
	v_cvt_pk_bf16_f32 v97, v122, v123
	v_cvt_pk_bf16_f32 v98, v124, v125
	v_cvt_pk_bf16_f32 v99, v126, v127
	v_mfma_f32_32x32x16_bf16 v[0:15], v[100:103], v[144:147], v[0:15]
	v_add_f32_e32 v64, v64, v118
	v_add_f32_e32 v65, v65, v134
	v_add_f32_e32 v64, v64, v119
	v_add_f32_e32 v65, v65, v135
	v_cvt_pk_bf16_f32 v100, v136, v137
	v_cvt_pk_bf16_f32 v101, v138, v139
	v_cvt_pk_bf16_f32 v102, v140, v141
	v_cvt_pk_bf16_f32 v103, v142, v95
	ds_read_b64_tr_b16 v[104:105], v245 offset:32768
	ds_read_b64_tr_b16 v[106:107], v245 offset:34048
	ds_read_b64_tr_b16 v[110:111], v245 offset:34112
	ds_read_b64_tr_b16 v[108:109], v245 offset:32832
	s_waitcnt lgkmcnt(2)
	v_mfma_f32_32x32x16_bf16 v[48:63], v[96:99], v[104:107], v[48:63]
	v_add_f32_e32 v64, v64, v120
	v_add_f32_e32 v65, v65, v136
	v_add_f32_e32 v64, v64, v121
	v_add_f32_e32 v65, v65, v137
	v_mfma_f32_32x32x16_bf16 v[16:31], v[100:103], v[104:107], v[16:31]
	v_add_f32_e32 v64, v64, v122
	v_add_f32_e32 v65, v65, v138
	v_add_f32_e32 v64, v64, v123
	v_add_f32_e32 v65, v65, v139
	s_waitcnt lgkmcnt(0)
	v_mfma_f32_32x32x16_bf16 v[32:47], v[96:99], v[108:111], v[32:47]
	v_add_f32_e32 v64, v64, v124
	v_add_f32_e32 v65, v65, v140
	v_add_f32_e32 v64, v64, v125
	v_add_f32_e32 v65, v65, v141
	v_mfma_f32_32x32x16_bf16 v[0:15], v[100:103], v[108:111], v[0:15]
	v_add_f32_e32 v64, v64, v126
	v_add_f32_e32 v65, v65, v142
	v_add_f32_e32 v64, v64, v127
	v_add_f32_e32 v65, v65, v95
	s_and_b64 vcc, exec, s[2:3]
	s_cbranch_vccz .LBB0_736
	s_bitcmp1_b32 s15, 0
	s_cselect_b32 s2, 0x9400, 0
	v_add_u32_e32 v96, s2, v236
	v_add_u32_e32 v97, v96, v238
	v_add_u32_e32 v96, v96, v237
	s_waitcnt vmcnt(0)
	ds_write_b128 v96, v[160:163]
	ds_write_b128 v97, v[164:167] offset:17408
	ds_write_b128 v96, v[168:171] offset:8704
	ds_write_b128 v97, v[172:175] offset:27648
	s_branch .LBB0_736
